# v053 + m3 compact item mapping at the last layer (1024 valid items in 4 rounds instead of 5)
# speedup vs baseline: 1.0105x; 1.0016x over previous
; __device__ void phase_m3(const P& p, int l) {
;     ...
;   for (int it = BIDX; it < 16 * 68; it += gridDim.x) {
;     int bh = it / 68, blk = it % 68, b = bh >> 2, h = bh & 3;
;     if (!need_ctx && blk < 4) continue;
;     int R0 = b * TPB + blk * 64;
.LBB0_460:
	s_and_b64 vcc, exec, s[96:97]
	s_cbranch_vccz .Lm3_norm
	v_readlane_b32 s0, v249, 48
	s_nop 3
	s_cmpk_lg_i32 s0, 0x100
	s_cbranch_scc1 .Lm3_norm
	s_cmpk_lt_i32 s95, 0x400
	s_cbranch_scc1 .Lm3_compact
	s_movk_i32 s95, 0x440
	s_branch .LBB0_459
.Lm3_compact:
	s_lshr_b32 s0, s95, 6
	s_and_b32 s1, s95, 63
	s_add_i32 s1, s1, 4
	s_branch .Lm3_have

; __device__ void phase_m3(const P& p, int l) {
;     ...
;     int bh = it / 68, blk = it % 68, b = bh >> 2, h = bh & 3;
;     if (!need_ctx && blk < 4) continue;
;     int R0 = b * TPB + blk * 64;
;     int itemd[2];
;     itemd[0] = (bh * 2 + 0) * 68 + chunk_index(0, blk);
;     itemd[1] = (bh * 2 + 1) * 68 + chunk_index(1, blk);
;     bf16x8 lq[2], lk[2], lv[2];
; #pragma unroll
;     for (int i = 0; i < 2; ++i) {
;       int c = TIDX + i * NTHR, s = c >> 4, part = c & 15;
;       lq[i] = *(const bf16x8*)(qkc + (size_t)(R0 + s) * 1024 + h * 128 + part * 8);
;       lk[i] = *(const bf16x8*)(qkc + (size_t)(R0 + s) * 1024 + 512 + h * 128 + part * 8);
;       int c2s = c & 63, c2p = c >> 6;
;       lv[i] = *(const bf16x8*)(proj + (size_t)(R0 + c2s) * NP + C_DV + h * 128 + c2p * 8);
;     }
;     float lnin = 0.f;
;     if (TIDX < 256) lnin = ((const float*)(ws + O_NIN))[(size_t)itemd[TIDX >> 7] * 128 + (TIDX & 127)];
;     const float m_in = ((const float*)(ws + O_MIN))[itemd[wid >> 2]];
.Lm3_have:
	s_lshr_b32 s2, s0, 2
	s_mul_i32 s6, s2, 0x1100
	s_lshl_b32 s2, s1, 6
	s_add_i32 s6, s6, s2
	v_add_u32_e32 v4, s6, v130
	s_and_b32 s5, s0, 3
	v_ashrrev_i32_e32 v5, 31, v4
	v_add_u32_e32 v6, s6, v131
	s_cmp_gt_i32 s1, 3
	v_or_b32_e32 v0, s6, v85
	v_mov_b64_e32 v[2:3], s[86:87]
	s_movk_i32 s2, 0x3a00
	v_lshlrev_b64 v[4:5], 11, v[4:5]
	v_ashrrev_i32_e32 v7, 31, v6
	s_cselect_b32 s4, 0x47, 3
	v_mad_i64_i32 v[2:3], s[2:3], v0, s2, v[2:3]
	s_lshl_b32 s20, s5, 8
	v_lshl_add_u64 v[4:5], s[36:37], 0, v[4:5]
	v_lshlrev_b64 v[6:7], 11, v[6:7]
	v_lshl_add_u64 v[2:3], v[2:3], 0, s[20:21]
	s_mov_b64 s[2:3], 0x2c80
	v_lshl_add_u64 v[4:5], v[4:5], 0, s[20:21]
	v_mov_b32_e32 v97, v1
	v_lshl_add_u64 v[6:7], s[36:37], 0, v[6:7]
	v_lshl_add_u64 v[2:3], v[2:3], 0, s[2:3]
	v_lshl_add_u64 v[4:5], v[4:5], 0, v[96:97]
	v_lshl_add_u64 v[6:7], v[6:7], 0, s[20:21]
	global_load_dwordx4 v[38:41], v[4:5], off
	global_load_dwordx4 v[42:45], v[4:5], off offset:1024
	v_lshl_add_u64 v[4:5], v[86:87], 1, v[2:3]
	v_lshl_add_u64 v[6:7], v[6:7], 0, v[96:97]
	global_load_dwordx4 v[46:49], v[4:5], off
	global_load_dwordx4 v[50:53], v[6:7], off
	v_lshl_add_u64 v[2:3], v[88:89], 1, v[2:3]
	global_load_dwordx4 v[54:57], v[6:7], off offset:1024
	global_load_dwordx4 v[34:37], v[2:3], off
	s_mulk_i32 s0, 0x88
	s_add_i32 s2, s0, s1
	s_sub_i32 s0, s0, s1
	s_add_i32 s3, s0, s4
	s_addk_i32 s3, 0x44
	v_mov_b32_e32 v60, 0
	s_and_saveexec_b64 s[0:1], s[38:39]
	s_cbranch_execz .LBB0_463
	v_mov_b32_e32 v0, s2
	v_mov_b32_e32 v2, s3
	v_cmp_eq_u32_e32 vcc, 1, v116
	s_nop 1
	v_cndmask_b32_e32 v2, v0, v2, vcc
	v_ashrrev_i32_e32 v3, 31, v2
	v_lshlrev_b64 v[2:3], 9, v[2:3]
	v_lshl_add_u64 v[2:3], v[82:83], 0, v[2:3]
	global_load_dword v60, v[2:3], off
